# light combination + S3 epilogue gelu exponent argument in 3 VALU ops instead of 5 (f32, merged constants)
# baseline (speedup 1.0000x reference)
; __device__ __forceinline__ unsigned cvt_pk_bf16(float lo, float hi) { const cvt_f32x2_t v = {lo, hi}; const cvt_bf16x2_t b = __builtin_convertvector(v, cvt_bf16x2_t); return __builtin_bit_cast(unsigned, b); }
; __device__ __forceinline__ float gelu_tanh(float y) {
;     const float t = 1.5957691216057308f * (y + 0.044715f * y * y * y);
;     return y * __builtin_amdgcn_rcpf(1.0f + __builtin_amdgcn_exp2f(-LOG2E * t));
; }
;     __device__ __forceinline__ void operator()(const f32x4 (&acc)[2][2][4][2], const Unit& u, int wr, int wc, int fr, int fq) const {
;         const int gidx = u.pm >> 3;
; #pragma unroll
;         for (int ai = 0; ai < 2; ++ai)
; #pragma unroll
;             for (int m = 0; m < 4; ++m) {
;                 const int bc = (u.pm & 7) * 256 + ai * 128 + wr * 64 + m * 16 + fr, b = bc >> 6, ch = bc & 63;
; #pragma unroll
;                 for (int bj = 0; bj < 2; ++bj) {
;                     const int nl = (u.pn & 1) * 256 + bj * 128 + wc * 32 + 8 * fq, tau = nl >> 4, c8 = nl & 15;
;                     const f32x4 a = acc[ai][bj][m][0], c = acc[ai][bj][m][1];
;                     u32x4 w; w.x = cvt_pk_bf16(gelu_tanh(a[0]), gelu_tanh(a[1])); w.y = cvt_pk_bf16(gelu_tanh(a[2]), gelu_tanh(a[3]));
;                     w.z = cvt_pk_bf16(gelu_tanh(c[0]), gelu_tanh(c[1])); w.w = cvt_pk_bf16(gelu_tanh(c[2]), gelu_tanh(c[3]));
;                     *(u32x4*)(Z + (size_t)(b * SEQ + ch * CT + tau) * SW + gidx * 16 + c8) = w;
.LBB0_437:
	v_mov_b32_e32 v228, 0xc0135761
	v_mul_f32_e32 v146, v124, v124
	v_mul_f32_e32 v147, v125, v125
	v_fmamk_f32 v146, v146, 0xbdd2d3e7, v228
	v_fmamk_f32 v147, v147, 0xbdd2d3e7, v228
	v_mul_f32_e32 v146, v124, v146
	v_mul_f32_e32 v147, v125, v147
	v_exp_f32_e32 v146, v146
	v_exp_f32_e32 v147, v147
	s_lshl_b32 s4, s50, 8
	s_and_b32 s4, s4, 0x700
	v_add_f32_e32 v146, 1.0, v146
	v_add_f32_e32 v147, 1.0, v147
	v_rcp_f32_e32 v146, v146
	v_rcp_f32_e32 v147, v147
	s_add_i32 s6, s4, s63
	s_lshl_b32 s4, s51, 8
	s_and_b32 s4, s4, 0x100
	v_pk_mul_f32 v[124:125], v[124:125], v[146:147]
	v_mov_b32_e32 v148, v141
	v_cvt_pk_bf16_f32 v124, v124, v125
	v_mul_f32_e32 v125, v126, v126
	v_fmamk_f32 v125, v125, 0xbdd2d3e7, v228
	v_mul_f32_e32 v125, v126, v125
	v_exp_f32_e32 v125, v125
	v_mov_b32_e32 v145, v140
	s_or_b32 s4, s4, s64
	v_add_f32_e32 v125, 1.0, v125
	v_rcp_f32_e32 v146, v125
	v_mul_f32_e32 v125, v127, v127
	v_fmamk_f32 v125, v125, 0xbdd2d3e7, v228
	v_mul_f32_e32 v125, v127, v125
	v_exp_f32_e32 v125, v125
	v_lshl_add_u32 v149, v148, 3, s4
	v_ashrrev_i32_e32 v144, 4, v149
	v_add_lshl_u32 v145, s6, v145, 5
	v_add_f32_e32 v125, 1.0, v125
	v_rcp_f32_e32 v147, v125
	s_lshl_b32 s4, s50, 1
	s_and_b32 s4, s4, -16
	s_ashr_i32 s5, s4, 31
	v_pk_mul_f32 v[126:127], v[126:127], v[146:147]
	s_lshl_b64 s[4:5], s[4:5], 1
	v_cvt_pk_bf16_f32 v125, v126, v127
	v_mul_f32_e32 v126, v120, v120
	v_mul_f32_e32 v127, v121, v121
	v_fmamk_f32 v126, v126, 0xbdd2d3e7, v228
	v_fmamk_f32 v127, v127, 0xbdd2d3e7, v228
	v_mul_f32_e32 v126, v120, v126
	v_mul_f32_e32 v127, v121, v127
	v_exp_f32_e32 v126, v126
	v_exp_f32_e32 v127, v127
	s_mov_b32 s80, 0xeb1c432d
	s_and_b64 vcc, exec, s[42:43]
	v_add_f32_e32 v126, 1.0, v126
	v_add_f32_e32 v127, 1.0, v127
	v_rcp_f32_e32 v126, v126
	v_rcp_f32_e32 v127, v127
	s_mov_b32 s81, 0xbf1a36e2
	v_pk_mul_f32 v[120:121], v[120:121], v[126:127]
	s_nop 0
	v_cvt_pk_bf16_f32 v126, v120, v121
	v_mul_f32_e32 v120, v122, v122
	v_mul_f32_e32 v121, v123, v123
	v_fmamk_f32 v120, v120, 0xbdd2d3e7, v228
	v_fmamk_f32 v121, v121, 0xbdd2d3e7, v228
	v_mul_f32_e32 v120, v122, v120
	v_mul_f32_e32 v121, v123, v121
	v_exp_f32_e32 v120, v120
	v_exp_f32_e32 v121, v121
	v_add_f32_e32 v120, 1.0, v120
	v_add_f32_e32 v121, 1.0, v121
	v_rcp_f32_e32 v120, v120
	v_rcp_f32_e32 v121, v121
	s_nop 0
	v_pk_mul_f32 v[120:121], v[122:123], v[120:121]
	s_nop 0
	v_cvt_pk_bf16_f32 v127, v120, v121
	v_add_u32_e32 v120, v144, v145
	v_ashrrev_i32_e32 v121, 31, v120
	v_lshlrev_b64 v[120:121], 10, v[120:121]
	v_lshl_add_u64 v[120:121], s[46:47], 0, v[120:121]
	v_lshlrev_b32_e32 v122, 4, v148
	v_lshl_add_u64 v[120:121], v[120:121], 0, s[4:5]
	v_and_b32_e32 v192, 16, v122
	v_lshl_add_u64 v[120:121], v[120:121], 0, v[192:193]
	global_store_dwordx4 v[120:121], v[124:127], off
	v_mul_f32_e32 v121, v116, v116
	v_fmamk_f32 v121, v121, 0xbdd2d3e7, v228
	v_mul_f32_e32 v121, v116, v121
	v_exp_f32_e32 v121, v121
	v_add_u32_e32 v120, 0x80, v149
	v_ashrrev_i32_e32 v120, 4, v120
	v_add_f32_e32 v121, 1.0, v121
	v_rcp_f32_e32 v122, v121
	v_mul_f32_e32 v121, v117, v117
	v_fmamk_f32 v121, v121, 0xbdd2d3e7, v228
	v_mul_f32_e32 v121, v117, v121
	v_exp_f32_e32 v121, v121
	s_nop 0
	v_add_f32_e32 v121, 1.0, v121
	v_rcp_f32_e32 v123, v121
	s_nop 0
	v_pk_mul_f32 v[116:117], v[116:117], v[122:123]
	s_nop 0
	v_cvt_pk_bf16_f32 v116, v116, v117
	v_mul_f32_e32 v117, v118, v118
	v_fmamk_f32 v117, v117, 0xbdd2d3e7, v228
	v_mul_f32_e32 v117, v118, v117
	v_exp_f32_e32 v117, v117
	s_nop 0
	v_add_f32_e32 v117, 1.0, v117
	v_rcp_f32_e32 v122, v117
	v_mul_f32_e32 v117, v119, v119
	v_fmamk_f32 v117, v117, 0xbdd2d3e7, v228
	v_mul_f32_e32 v117, v119, v117
	v_exp_f32_e32 v117, v117
	s_nop 0
	v_add_f32_e32 v117, 1.0, v117
	v_rcp_f32_e32 v123, v117
	s_nop 0
	v_pk_mul_f32 v[118:119], v[118:119], v[122:123]
	s_nop 0
	v_cvt_pk_bf16_f32 v117, v118, v119
	v_mul_f32_e32 v118, v112, v112
	v_mul_f32_e32 v119, v113, v113
	v_fmamk_f32 v118, v118, 0xbdd2d3e7, v228
	v_fmamk_f32 v119, v119, 0xbdd2d3e7, v228
	v_mul_f32_e32 v118, v112, v118
	v_mul_f32_e32 v119, v113, v119
	v_exp_f32_e32 v118, v118
	v_exp_f32_e32 v119, v119
	v_add_f32_e32 v118, 1.0, v118
	v_add_f32_e32 v119, 1.0, v119
	v_rcp_f32_e32 v118, v118
	v_rcp_f32_e32 v119, v119
	s_nop 0
	v_pk_mul_f32 v[112:113], v[112:113], v[118:119]
	s_nop 0
	v_cvt_pk_bf16_f32 v118, v112, v113
	v_mul_f32_e32 v112, v114, v114
	v_mul_f32_e32 v113, v115, v115
	v_fmamk_f32 v112, v112, 0xbdd2d3e7, v228
	v_fmamk_f32 v113, v113, 0xbdd2d3e7, v228
	v_mul_f32_e32 v112, v114, v112
	v_mul_f32_e32 v113, v115, v113
	v_exp_f32_e32 v112, v112
	v_exp_f32_e32 v113, v113
	v_add_f32_e32 v112, 1.0, v112
	v_add_f32_e32 v113, 1.0, v113
	v_rcp_f32_e32 v112, v112
	v_rcp_f32_e32 v113, v113
	s_nop 0
	v_pk_mul_f32 v[112:113], v[114:115], v[112:113]
	s_nop 0
	v_cvt_pk_bf16_f32 v119, v112, v113
	v_add_u32_e32 v112, v120, v145
	v_ashrrev_i32_e32 v113, 31, v112
	v_lshlrev_b64 v[112:113], 10, v[112:113]
	v_lshl_add_u64 v[112:113], s[46:47], 0, v[112:113]
	v_lshl_add_u64 v[112:113], v[112:113], 0, s[4:5]
	v_lshl_add_u64 v[112:113], v[112:113], 0, v[192:193]
	global_store_dwordx4 v[112:113], v[116:119], off
	v_mul_f32_e32 v112, v108, v108
	v_mul_f32_e32 v113, v109, v109
	v_fmamk_f32 v112, v112, 0xbdd2d3e7, v228
	v_fmamk_f32 v113, v113, 0xbdd2d3e7, v228
	v_mul_f32_e32 v112, v108, v112
	v_mul_f32_e32 v113, v109, v113
	v_exp_f32_e32 v112, v112
	v_exp_f32_e32 v113, v113
	v_add_u32_e32 v114, 0x200, v145
	v_add_f32_e32 v112, 1.0, v112
	v_add_f32_e32 v113, 1.0, v113
	v_rcp_f32_e32 v112, v112
	v_rcp_f32_e32 v113, v113
	s_nop 0
	v_pk_mul_f32 v[108:109], v[108:109], v[112:113]
	s_nop 0
	v_cvt_pk_bf16_f32 v108, v108, v109
	v_mul_f32_e32 v109, v110, v110
; __device__ __forceinline__ unsigned cvt_pk_bf16(float lo, float hi) { const cvt_f32x2_t v = {lo, hi}; const cvt_bf16x2_t b = __builtin_convertvector(v, cvt_bf16x2_t); return __builtin_bit_cast(unsigned, b); }
; __device__ __forceinline__ float gelu_tanh(float y) {
;     const float t = 1.5957691216057308f * (y + 0.044715f * y * y * y);
;     return y * __builtin_amdgcn_rcpf(1.0f + __builtin_amdgcn_exp2f(-LOG2E * t));
;     __device__ __forceinline__ void operator()(const f32x4 (&acc)[2][2][4][2], const Unit& u, int wr, int wc, int fr, int fq) const {
;     ...
;                 const int bc = (u.pm & 7) * 256 + ai * 128 + wr * 64 + m * 16 + fr, b = bc >> 6, ch = bc & 63;
; #pragma unroll
;                 for (int bj = 0; bj < 2; ++bj) {
;                     const int nl = (u.pn & 1) * 256 + bj * 128 + wc * 32 + 8 * fq, tau = nl >> 4, c8 = nl & 15;
;                     const f32x4 a = acc[ai][bj][m][0], c = acc[ai][bj][m][1];
;                     u32x4 w; w.x = cvt_pk_bf16(gelu_tanh(a[0]), gelu_tanh(a[1])); w.y = cvt_pk_bf16(gelu_tanh(a[2]), gelu_tanh(a[3]));
;                     w.z = cvt_pk_bf16(gelu_tanh(c[0]), gelu_tanh(c[1])); w.w = cvt_pk_bf16(gelu_tanh(c[2]), gelu_tanh(c[3]));
;                     *(u32x4*)(Z + (size_t)(b * SEQ + ch * CT + tau) * SW + gidx * 16 + c8) = w;
	v_fmamk_f32 v109, v109, 0xbdd2d3e7, v228
	v_mul_f32_e32 v109, v110, v109
	v_exp_f32_e32 v109, v109
	s_nop 0
	v_add_f32_e32 v109, 1.0, v109
	v_rcp_f32_e32 v112, v109
	v_mul_f32_e32 v109, v111, v111
	v_fmamk_f32 v109, v109, 0xbdd2d3e7, v228
	v_mul_f32_e32 v109, v111, v109
	v_exp_f32_e32 v109, v109
	s_nop 0
	v_add_f32_e32 v109, 1.0, v109
	v_rcp_f32_e32 v113, v109
	s_nop 0
	v_pk_mul_f32 v[110:111], v[110:111], v[112:113]
	s_nop 0
	v_cvt_pk_bf16_f32 v109, v110, v111
	v_mul_f32_e32 v110, v104, v104
	v_mul_f32_e32 v111, v105, v105
	v_fmamk_f32 v110, v110, 0xbdd2d3e7, v228
	v_fmamk_f32 v111, v111, 0xbdd2d3e7, v228
	v_mul_f32_e32 v110, v104, v110
	v_mul_f32_e32 v111, v105, v111
	v_exp_f32_e32 v110, v110
	v_exp_f32_e32 v111, v111
	v_add_f32_e32 v110, 1.0, v110
	v_add_f32_e32 v111, 1.0, v111
	v_rcp_f32_e32 v110, v110
	v_rcp_f32_e32 v111, v111
	s_nop 0
	v_pk_mul_f32 v[104:105], v[104:105], v[110:111]
	s_nop 0
	v_cvt_pk_bf16_f32 v110, v104, v105
	v_mul_f32_e32 v104, v106, v106
	v_mul_f32_e32 v105, v107, v107
	v_fmamk_f32 v104, v104, 0xbdd2d3e7, v228
	v_fmamk_f32 v105, v105, 0xbdd2d3e7, v228
	v_mul_f32_e32 v104, v106, v104
	v_mul_f32_e32 v105, v107, v105
	v_exp_f32_e32 v104, v104
	v_exp_f32_e32 v105, v105
	v_add_f32_e32 v104, 1.0, v104
	v_add_f32_e32 v105, 1.0, v105
	v_rcp_f32_e32 v104, v104
	v_rcp_f32_e32 v105, v105
	s_nop 0
	v_pk_mul_f32 v[104:105], v[106:107], v[104:105]
	s_nop 0
	v_cvt_pk_bf16_f32 v111, v104, v105
	v_add_u32_e32 v104, v144, v114
	v_ashrrev_i32_e32 v105, 31, v104
	v_lshlrev_b64 v[104:105], 10, v[104:105]
	v_lshl_add_u64 v[104:105], s[46:47], 0, v[104:105]
	v_lshl_add_u64 v[104:105], v[104:105], 0, s[4:5]
	v_lshl_add_u64 v[104:105], v[104:105], 0, v[192:193]
	global_store_dwordx4 v[104:105], v[108:111], off
	v_mul_f32_e32 v104, v100, v100
	v_mul_f32_e32 v105, v101, v101
	v_fmamk_f32 v104, v104, 0xbdd2d3e7, v228
	v_fmamk_f32 v105, v105, 0xbdd2d3e7, v228
	v_mul_f32_e32 v104, v100, v104
	v_mul_f32_e32 v105, v101, v105
	v_exp_f32_e32 v104, v104
	v_exp_f32_e32 v105, v105
	v_add_f32_e32 v104, 1.0, v104
	v_add_f32_e32 v105, 1.0, v105
	v_rcp_f32_e32 v104, v104
	v_rcp_f32_e32 v105, v105
	s_nop 0
	v_pk_mul_f32 v[100:101], v[100:101], v[104:105]
	s_nop 0
	v_cvt_pk_bf16_f32 v100, v100, v101
	v_mul_f32_e32 v101, v102, v102
	v_fmamk_f32 v101, v101, 0xbdd2d3e7, v228
	v_mul_f32_e32 v101, v102, v101
	v_exp_f32_e32 v101, v101
	s_nop 0
	v_add_f32_e32 v101, 1.0, v101
	v_rcp_f32_e32 v104, v101
	v_mul_f32_e32 v101, v103, v103
	v_fmamk_f32 v101, v101, 0xbdd2d3e7, v228
	v_mul_f32_e32 v101, v103, v101
	v_exp_f32_e32 v101, v101
	s_nop 0
	v_add_f32_e32 v101, 1.0, v101
	v_rcp_f32_e32 v105, v101
	s_nop 0
	v_pk_mul_f32 v[102:103], v[102:103], v[104:105]
	s_nop 0
	v_cvt_pk_bf16_f32 v101, v102, v103
	v_mul_f32_e32 v102, v96, v96
	v_mul_f32_e32 v103, v97, v97
	v_fmamk_f32 v102, v102, 0xbdd2d3e7, v228
	v_fmamk_f32 v103, v103, 0xbdd2d3e7, v228
	v_mul_f32_e32 v102, v96, v102
	v_mul_f32_e32 v103, v97, v103
	v_exp_f32_e32 v102, v102
	v_exp_f32_e32 v103, v103
	v_add_f32_e32 v102, 1.0, v102
	v_add_f32_e32 v103, 1.0, v103
	v_rcp_f32_e32 v102, v102
	v_rcp_f32_e32 v103, v103
	s_nop 0
	v_pk_mul_f32 v[96:97], v[96:97], v[102:103]
	s_nop 0
	v_cvt_pk_bf16_f32 v102, v96, v97
	v_mul_f32_e32 v96, v98, v98
	v_mul_f32_e32 v97, v99, v99
	v_fmamk_f32 v96, v96, 0xbdd2d3e7, v228
	v_fmamk_f32 v97, v97, 0xbdd2d3e7, v228
	v_mul_f32_e32 v96, v98, v96
	v_mul_f32_e32 v97, v99, v97
	v_exp_f32_e32 v96, v96
	v_exp_f32_e32 v97, v97
	v_add_f32_e32 v96, 1.0, v96
	v_add_f32_e32 v97, 1.0, v97
	v_rcp_f32_e32 v96, v96
	v_rcp_f32_e32 v97, v97
	s_nop 0
	v_pk_mul_f32 v[96:97], v[98:99], v[96:97]
	s_nop 0
	v_cvt_pk_bf16_f32 v103, v96, v97
	v_add_u32_e32 v96, v120, v114
	v_ashrrev_i32_e32 v97, 31, v96
	v_lshlrev_b64 v[96:97], 10, v[96:97]
	v_lshl_add_u64 v[96:97], s[46:47], 0, v[96:97]
	v_lshl_add_u64 v[96:97], v[96:97], 0, s[4:5]
	v_lshl_add_u64 v[96:97], v[96:97], 0, v[192:193]
	global_store_dwordx4 v[96:97], v[100:103], off
	v_mul_f32_e32 v96, v92, v92
	v_mul_f32_e32 v97, v93, v93
	v_fmamk_f32 v96, v96, 0xbdd2d3e7, v228
	v_fmamk_f32 v97, v97, 0xbdd2d3e7, v228
	v_mul_f32_e32 v96, v92, v96
	v_mul_f32_e32 v97, v93, v97
	v_exp_f32_e32 v96, v96
	v_exp_f32_e32 v97, v97
	v_add_u32_e32 v98, 0x400, v145
	v_add_f32_e32 v96, 1.0, v96
	v_add_f32_e32 v97, 1.0, v97
	v_rcp_f32_e32 v96, v96
	v_rcp_f32_e32 v97, v97
	s_nop 0
	v_pk_mul_f32 v[92:93], v[92:93], v[96:97]
	s_nop 0
	v_cvt_pk_bf16_f32 v92, v92, v93
	v_mul_f32_e32 v93, v94, v94
	v_fmamk_f32 v93, v93, 0xbdd2d3e7, v228
	v_mul_f32_e32 v93, v94, v93
	v_exp_f32_e32 v93, v93
	s_nop 0
	v_add_f32_e32 v93, 1.0, v93
	v_rcp_f32_e32 v96, v93
	v_mul_f32_e32 v93, v95, v95
	v_fmamk_f32 v93, v93, 0xbdd2d3e7, v228
	v_mul_f32_e32 v93, v95, v93
	v_exp_f32_e32 v93, v93
	s_nop 0
	v_add_f32_e32 v93, 1.0, v93
	v_rcp_f32_e32 v97, v93
	s_nop 0
	v_pk_mul_f32 v[94:95], v[94:95], v[96:97]
	s_nop 0
	v_cvt_pk_bf16_f32 v93, v94, v95
	v_mul_f32_e32 v94, v88, v88
	v_mul_f32_e32 v95, v89, v89
	v_fmamk_f32 v94, v94, 0xbdd2d3e7, v228
	v_fmamk_f32 v95, v95, 0xbdd2d3e7, v228
	v_mul_f32_e32 v94, v88, v94
	v_mul_f32_e32 v95, v89, v95
	v_exp_f32_e32 v94, v94
	v_exp_f32_e32 v95, v95
	v_add_f32_e32 v94, 1.0, v94
	v_add_f32_e32 v95, 1.0, v95
	v_rcp_f32_e32 v94, v94
	v_rcp_f32_e32 v95, v95
	s_nop 0
	v_pk_mul_f32 v[88:89], v[88:89], v[94:95]
	s_nop 0
	v_cvt_pk_bf16_f32 v94, v88, v89
	v_mul_f32_e32 v88, v90, v90
	v_mul_f32_e32 v89, v91, v91
	v_fmamk_f32 v88, v88, 0xbdd2d3e7, v228
	v_fmamk_f32 v89, v89, 0xbdd2d3e7, v228
	v_mul_f32_e32 v88, v90, v88
	v_mul_f32_e32 v89, v91, v89
	v_exp_f32_e32 v88, v88
	v_exp_f32_e32 v89, v89
	v_add_f32_e32 v88, 1.0, v88
	v_add_f32_e32 v89, 1.0, v89
	v_rcp_f32_e32 v88, v88
; __device__ __forceinline__ unsigned cvt_pk_bf16(float lo, float hi) { const cvt_f32x2_t v = {lo, hi}; const cvt_bf16x2_t b = __builtin_convertvector(v, cvt_bf16x2_t); return __builtin_bit_cast(unsigned, b); }
; __device__ __forceinline__ float gelu_tanh(float y) {
;     const float t = 1.5957691216057308f * (y + 0.044715f * y * y * y);
;     return y * __builtin_amdgcn_rcpf(1.0f + __builtin_amdgcn_exp2f(-LOG2E * t));
;     __device__ __forceinline__ void operator()(const f32x4 (&acc)[2][2][4][2], const Unit& u, int wr, int wc, int fr, int fq) const {
;     ...
;                 const int bc = (u.pm & 7) * 256 + ai * 128 + wr * 64 + m * 16 + fr, b = bc >> 6, ch = bc & 63;
; #pragma unroll
;                 for (int bj = 0; bj < 2; ++bj) {
;                     const int nl = (u.pn & 1) * 256 + bj * 128 + wc * 32 + 8 * fq, tau = nl >> 4, c8 = nl & 15;
;                     const f32x4 a = acc[ai][bj][m][0], c = acc[ai][bj][m][1];
;                     u32x4 w; w.x = cvt_pk_bf16(gelu_tanh(a[0]), gelu_tanh(a[1])); w.y = cvt_pk_bf16(gelu_tanh(a[2]), gelu_tanh(a[3]));
;                     w.z = cvt_pk_bf16(gelu_tanh(c[0]), gelu_tanh(c[1])); w.w = cvt_pk_bf16(gelu_tanh(c[2]), gelu_tanh(c[3]));
;                     *(u32x4*)(Z + (size_t)(b * SEQ + ch * CT + tau) * SW + gidx * 16 + c8) = w;
	v_rcp_f32_e32 v89, v89
	s_nop 0
	v_pk_mul_f32 v[88:89], v[90:91], v[88:89]
	s_nop 0
	v_cvt_pk_bf16_f32 v95, v88, v89
	v_add_u32_e32 v88, v144, v98
	v_ashrrev_i32_e32 v89, 31, v88
	v_lshlrev_b64 v[88:89], 10, v[88:89]
	v_lshl_add_u64 v[88:89], s[46:47], 0, v[88:89]
	v_lshl_add_u64 v[88:89], v[88:89], 0, s[4:5]
	v_lshl_add_u64 v[88:89], v[88:89], 0, v[192:193]
	global_store_dwordx4 v[88:89], v[92:95], off
	v_mul_f32_e32 v88, v84, v84
	v_mul_f32_e32 v89, v85, v85
	v_fmamk_f32 v88, v88, 0xbdd2d3e7, v228
	v_fmamk_f32 v89, v89, 0xbdd2d3e7, v228
	v_mul_f32_e32 v88, v84, v88
	v_mul_f32_e32 v89, v85, v89
	v_exp_f32_e32 v88, v88
	v_exp_f32_e32 v89, v89
	v_add_f32_e32 v88, 1.0, v88
	v_add_f32_e32 v89, 1.0, v89
	v_rcp_f32_e32 v88, v88
	v_rcp_f32_e32 v89, v89
	s_nop 0
	v_pk_mul_f32 v[84:85], v[84:85], v[88:89]
	s_nop 0
	v_cvt_pk_bf16_f32 v84, v84, v85
	v_mul_f32_e32 v85, v86, v86
	v_fmamk_f32 v85, v85, 0xbdd2d3e7, v228
	v_mul_f32_e32 v85, v86, v85
	v_exp_f32_e32 v85, v85
	s_nop 0
	v_add_f32_e32 v85, 1.0, v85
	v_rcp_f32_e32 v88, v85
	v_mul_f32_e32 v85, v87, v87
	v_fmamk_f32 v85, v85, 0xbdd2d3e7, v228
	v_mul_f32_e32 v85, v87, v85
	v_exp_f32_e32 v85, v85
	s_nop 0
	v_add_f32_e32 v85, 1.0, v85
	v_rcp_f32_e32 v89, v85
	s_nop 0
	v_pk_mul_f32 v[86:87], v[86:87], v[88:89]
	s_nop 0
	v_cvt_pk_bf16_f32 v85, v86, v87
	v_mul_f32_e32 v86, v80, v80
	v_mul_f32_e32 v87, v81, v81
	v_fmamk_f32 v86, v86, 0xbdd2d3e7, v228
	v_fmamk_f32 v87, v87, 0xbdd2d3e7, v228
	v_mul_f32_e32 v86, v80, v86
	v_mul_f32_e32 v87, v81, v87
	v_exp_f32_e32 v86, v86
	v_exp_f32_e32 v87, v87
	v_add_f32_e32 v86, 1.0, v86
	v_add_f32_e32 v87, 1.0, v87
	v_rcp_f32_e32 v86, v86
	v_rcp_f32_e32 v87, v87
	s_nop 0
	v_pk_mul_f32 v[80:81], v[80:81], v[86:87]
	s_nop 0
	v_cvt_pk_bf16_f32 v86, v80, v81
	v_mul_f32_e32 v80, v82, v82
	v_mul_f32_e32 v81, v83, v83
	v_fmamk_f32 v80, v80, 0xbdd2d3e7, v228
	v_fmamk_f32 v81, v81, 0xbdd2d3e7, v228
	v_mul_f32_e32 v80, v82, v80
	v_mul_f32_e32 v81, v83, v81
	v_exp_f32_e32 v80, v80
	v_exp_f32_e32 v81, v81
	v_add_f32_e32 v80, 1.0, v80
	v_add_f32_e32 v81, 1.0, v81
	v_rcp_f32_e32 v80, v80
	v_rcp_f32_e32 v81, v81
	s_nop 0
	v_pk_mul_f32 v[80:81], v[82:83], v[80:81]
	s_nop 0
	v_cvt_pk_bf16_f32 v87, v80, v81
	v_add_u32_e32 v80, v120, v98
	v_ashrrev_i32_e32 v81, 31, v80
	v_lshlrev_b64 v[80:81], 10, v[80:81]
	v_lshl_add_u64 v[80:81], s[46:47], 0, v[80:81]
	v_lshl_add_u64 v[80:81], v[80:81], 0, s[4:5]
	v_lshl_add_u64 v[80:81], v[80:81], 0, v[192:193]
	global_store_dwordx4 v[80:81], v[84:87], off
	v_mul_f32_e32 v80, v76, v76
	v_mul_f32_e32 v81, v77, v77
	v_fmamk_f32 v80, v80, 0xbdd2d3e7, v228
	v_fmamk_f32 v81, v81, 0xbdd2d3e7, v228
	v_mul_f32_e32 v80, v76, v80
	v_mul_f32_e32 v81, v77, v81
	v_exp_f32_e32 v80, v80
	v_exp_f32_e32 v81, v81
	v_add_u32_e32 v82, 0x600, v145
	v_add_f32_e32 v80, 1.0, v80
	v_add_f32_e32 v81, 1.0, v81
	v_rcp_f32_e32 v80, v80
	v_rcp_f32_e32 v81, v81
	s_nop 0
	v_pk_mul_f32 v[76:77], v[76:77], v[80:81]
	s_nop 0
	v_cvt_pk_bf16_f32 v76, v76, v77
	v_mul_f32_e32 v77, v78, v78
	v_fmamk_f32 v77, v77, 0xbdd2d3e7, v228
	v_mul_f32_e32 v77, v78, v77
	v_exp_f32_e32 v77, v77
	s_nop 0
	v_add_f32_e32 v77, 1.0, v77
	v_rcp_f32_e32 v80, v77
	v_mul_f32_e32 v77, v79, v79
	v_fmamk_f32 v77, v77, 0xbdd2d3e7, v228
	v_mul_f32_e32 v77, v79, v77
	v_exp_f32_e32 v77, v77
	s_nop 0
	v_add_f32_e32 v77, 1.0, v77
	v_rcp_f32_e32 v81, v77
	s_nop 0
	v_pk_mul_f32 v[78:79], v[78:79], v[80:81]
	s_nop 0
	v_cvt_pk_bf16_f32 v77, v78, v79
	v_mul_f32_e32 v78, v72, v72
	v_mul_f32_e32 v79, v73, v73
	v_fmamk_f32 v78, v78, 0xbdd2d3e7, v228
	v_fmamk_f32 v79, v79, 0xbdd2d3e7, v228
	v_mul_f32_e32 v78, v72, v78
	v_mul_f32_e32 v79, v73, v79
	v_exp_f32_e32 v78, v78
	v_exp_f32_e32 v79, v79
	v_add_f32_e32 v78, 1.0, v78
	v_add_f32_e32 v79, 1.0, v79
	v_rcp_f32_e32 v78, v78
	v_rcp_f32_e32 v79, v79
	s_nop 0
	v_pk_mul_f32 v[72:73], v[72:73], v[78:79]
	s_nop 0
	v_cvt_pk_bf16_f32 v78, v72, v73
	v_mul_f32_e32 v72, v74, v74
	v_mul_f32_e32 v73, v75, v75
	v_fmamk_f32 v72, v72, 0xbdd2d3e7, v228
	v_fmamk_f32 v73, v73, 0xbdd2d3e7, v228
	v_mul_f32_e32 v72, v74, v72
	v_mul_f32_e32 v73, v75, v73
	v_exp_f32_e32 v72, v72
	v_exp_f32_e32 v73, v73
	v_add_f32_e32 v72, 1.0, v72
	v_add_f32_e32 v73, 1.0, v73
	v_rcp_f32_e32 v72, v72
	v_rcp_f32_e32 v73, v73
	s_nop 0
	v_pk_mul_f32 v[72:73], v[74:75], v[72:73]
	s_nop 0
	v_cvt_pk_bf16_f32 v79, v72, v73
	v_add_u32_e32 v72, v144, v82
	v_ashrrev_i32_e32 v73, 31, v72
	v_lshlrev_b64 v[72:73], 10, v[72:73]
	v_lshl_add_u64 v[72:73], s[46:47], 0, v[72:73]
	v_lshl_add_u64 v[72:73], v[72:73], 0, s[4:5]
	v_lshl_add_u64 v[72:73], v[72:73], 0, v[192:193]
	global_store_dwordx4 v[72:73], v[76:79], off
	v_mul_f32_e32 v72, v68, v68
	v_mul_f32_e32 v73, v69, v69
	v_fmamk_f32 v72, v72, 0xbdd2d3e7, v228
	v_fmamk_f32 v73, v73, 0xbdd2d3e7, v228
	v_mul_f32_e32 v72, v68, v72
	v_mul_f32_e32 v73, v69, v73
	v_exp_f32_e32 v72, v72
	v_exp_f32_e32 v73, v73
	v_add_f32_e32 v72, 1.0, v72
	v_add_f32_e32 v73, 1.0, v73
	v_rcp_f32_e32 v72, v72
	v_rcp_f32_e32 v73, v73
	s_nop 0
	v_pk_mul_f32 v[68:69], v[68:69], v[72:73]
	s_nop 0
	v_cvt_pk_bf16_f32 v68, v68, v69
	v_mul_f32_e32 v69, v70, v70
	v_fmamk_f32 v69, v69, 0xbdd2d3e7, v228
	v_mul_f32_e32 v69, v70, v69
	v_exp_f32_e32 v69, v69
	s_nop 0
	v_add_f32_e32 v69, 1.0, v69
	v_rcp_f32_e32 v72, v69
	v_mul_f32_e32 v69, v71, v71
	v_fmamk_f32 v69, v69, 0xbdd2d3e7, v228
	v_mul_f32_e32 v69, v71, v69
	v_exp_f32_e32 v69, v69
	s_nop 0
	v_add_f32_e32 v69, 1.0, v69
	v_rcp_f32_e32 v73, v69
	s_nop 0
	v_pk_mul_f32 v[70:71], v[70:71], v[72:73]
	s_nop 0
	v_cvt_pk_bf16_f32 v69, v70, v71
	v_mul_f32_e32 v70, v64, v64
	v_mul_f32_e32 v71, v65, v65
	v_fmamk_f32 v70, v70, 0xbdd2d3e7, v228
	v_fmamk_f32 v71, v71, 0xbdd2d3e7, v228
; __device__ __forceinline__ unsigned cvt_pk_bf16(float lo, float hi) { const cvt_f32x2_t v = {lo, hi}; const cvt_bf16x2_t b = __builtin_convertvector(v, cvt_bf16x2_t); return __builtin_bit_cast(unsigned, b); }
; __device__ __forceinline__ float gelu_tanh(float y) {
;     const float t = 1.5957691216057308f * (y + 0.044715f * y * y * y);
;     return y * __builtin_amdgcn_rcpf(1.0f + __builtin_amdgcn_exp2f(-LOG2E * t));
;     __device__ __forceinline__ void operator()(const f32x4 (&acc)[2][2][4][2], const Unit& u, int wr, int wc, int fr, int fq) const {
;     ...
;                 const int bc = (u.pm & 7) * 256 + ai * 128 + wr * 64 + m * 16 + fr, b = bc >> 6, ch = bc & 63;
; #pragma unroll
;                 for (int bj = 0; bj < 2; ++bj) {
;                     const int nl = (u.pn & 1) * 256 + bj * 128 + wc * 32 + 8 * fq, tau = nl >> 4, c8 = nl & 15;
;                     const f32x4 a = acc[ai][bj][m][0], c = acc[ai][bj][m][1];
;                     u32x4 w; w.x = cvt_pk_bf16(gelu_tanh(a[0]), gelu_tanh(a[1])); w.y = cvt_pk_bf16(gelu_tanh(a[2]), gelu_tanh(a[3]));
;                     w.z = cvt_pk_bf16(gelu_tanh(c[0]), gelu_tanh(c[1])); w.w = cvt_pk_bf16(gelu_tanh(c[2]), gelu_tanh(c[3]));
;                     *(u32x4*)(Z + (size_t)(b * SEQ + ch * CT + tau) * SW + gidx * 16 + c8) = w;
	v_mul_f32_e32 v70, v64, v70
	v_mul_f32_e32 v71, v65, v71
	v_exp_f32_e32 v70, v70
	v_exp_f32_e32 v71, v71
	v_add_f32_e32 v70, 1.0, v70
	v_add_f32_e32 v71, 1.0, v71
	v_rcp_f32_e32 v70, v70
	v_rcp_f32_e32 v71, v71
	s_nop 0
	v_pk_mul_f32 v[64:65], v[64:65], v[70:71]
	s_nop 0
	v_cvt_pk_bf16_f32 v70, v64, v65
	v_mul_f32_e32 v64, v66, v66
	v_mul_f32_e32 v65, v67, v67
	v_fmamk_f32 v64, v64, 0xbdd2d3e7, v228
	v_fmamk_f32 v65, v65, 0xbdd2d3e7, v228
	v_mul_f32_e32 v64, v66, v64
	v_mul_f32_e32 v65, v67, v65
	v_exp_f32_e32 v64, v64
	v_exp_f32_e32 v65, v65
	v_add_f32_e32 v64, 1.0, v64
	v_add_f32_e32 v65, 1.0, v65
	v_rcp_f32_e32 v64, v64
	v_rcp_f32_e32 v65, v65
	s_nop 0
	v_pk_mul_f32 v[64:65], v[66:67], v[64:65]
	s_nop 0
	v_cvt_pk_bf16_f32 v71, v64, v65
	v_add_u32_e32 v64, v120, v82
	v_ashrrev_i32_e32 v65, 31, v64
	v_lshlrev_b64 v[64:65], 10, v[64:65]
	v_lshl_add_u64 v[64:65], s[46:47], 0, v[64:65]
	v_lshl_add_u64 v[64:65], v[64:65], 0, s[4:5]
	v_lshl_add_u64 v[64:65], v[64:65], 0, v[192:193]
	global_store_dwordx4 v[64:65], v[68:71], off
	v_mul_f32_e32 v64, v60, v60
	v_mul_f32_e32 v65, v61, v61
	v_fmamk_f32 v64, v64, 0xbdd2d3e7, v228
	v_fmamk_f32 v65, v65, 0xbdd2d3e7, v228
	v_mul_f32_e32 v64, v60, v64
	v_mul_f32_e32 v65, v61, v65
	v_exp_f32_e32 v64, v64
	v_exp_f32_e32 v65, v65
	v_add_u32_e32 v66, 0x1000, v145
	v_add_f32_e32 v64, 1.0, v64
	v_add_f32_e32 v65, 1.0, v65
	v_rcp_f32_e32 v64, v64
	v_rcp_f32_e32 v65, v65
	s_nop 0
	v_pk_mul_f32 v[60:61], v[60:61], v[64:65]
	s_nop 0
	v_cvt_pk_bf16_f32 v60, v60, v61
	v_mul_f32_e32 v61, v62, v62
	v_fmamk_f32 v61, v61, 0xbdd2d3e7, v228
	v_mul_f32_e32 v61, v62, v61
	v_exp_f32_e32 v61, v61
	s_nop 0
	v_add_f32_e32 v61, 1.0, v61
	v_rcp_f32_e32 v64, v61
	v_mul_f32_e32 v61, v63, v63
	v_fmamk_f32 v61, v61, 0xbdd2d3e7, v228
	v_mul_f32_e32 v61, v63, v61
	v_exp_f32_e32 v61, v61
	s_nop 0
	v_add_f32_e32 v61, 1.0, v61
	v_rcp_f32_e32 v65, v61
	s_nop 0
	v_pk_mul_f32 v[62:63], v[62:63], v[64:65]
	s_nop 0
	v_cvt_pk_bf16_f32 v61, v62, v63
	v_mul_f32_e32 v62, v56, v56
	v_mul_f32_e32 v63, v57, v57
	v_fmamk_f32 v62, v62, 0xbdd2d3e7, v228
	v_fmamk_f32 v63, v63, 0xbdd2d3e7, v228
	v_mul_f32_e32 v62, v56, v62
	v_mul_f32_e32 v63, v57, v63
	v_exp_f32_e32 v62, v62
	v_exp_f32_e32 v63, v63
	v_add_f32_e32 v62, 1.0, v62
	v_add_f32_e32 v63, 1.0, v63
	v_rcp_f32_e32 v62, v62
	v_rcp_f32_e32 v63, v63
	s_nop 0
	v_pk_mul_f32 v[56:57], v[56:57], v[62:63]
	s_nop 0
	v_cvt_pk_bf16_f32 v62, v56, v57
	v_mul_f32_e32 v56, v58, v58
	v_mul_f32_e32 v57, v59, v59
	v_fmamk_f32 v56, v56, 0xbdd2d3e7, v228
	v_fmamk_f32 v57, v57, 0xbdd2d3e7, v228
	v_mul_f32_e32 v56, v58, v56
	v_mul_f32_e32 v57, v59, v57
	v_exp_f32_e32 v56, v56
	v_exp_f32_e32 v57, v57
	v_add_f32_e32 v56, 1.0, v56
	v_add_f32_e32 v57, 1.0, v57
	v_rcp_f32_e32 v56, v56
	v_rcp_f32_e32 v57, v57
	s_nop 0
	v_pk_mul_f32 v[56:57], v[58:59], v[56:57]
	s_nop 0
	v_cvt_pk_bf16_f32 v63, v56, v57
	v_add_u32_e32 v56, v144, v66
	v_ashrrev_i32_e32 v57, 31, v56
	v_lshlrev_b64 v[56:57], 10, v[56:57]
	v_lshl_add_u64 v[56:57], s[46:47], 0, v[56:57]
	v_lshl_add_u64 v[56:57], v[56:57], 0, s[4:5]
	v_lshl_add_u64 v[56:57], v[56:57], 0, v[192:193]
	global_store_dwordx4 v[56:57], v[60:63], off
	v_mul_f32_e32 v56, v52, v52
	v_mul_f32_e32 v57, v53, v53
	v_fmamk_f32 v56, v56, 0xbdd2d3e7, v228
	v_fmamk_f32 v57, v57, 0xbdd2d3e7, v228
	v_mul_f32_e32 v56, v52, v56
	v_mul_f32_e32 v57, v53, v57
	v_exp_f32_e32 v56, v56
	v_exp_f32_e32 v57, v57
	v_add_f32_e32 v56, 1.0, v56
	v_add_f32_e32 v57, 1.0, v57
	v_rcp_f32_e32 v56, v56
	v_rcp_f32_e32 v57, v57
	s_nop 0
	v_pk_mul_f32 v[52:53], v[52:53], v[56:57]
	s_nop 0
	v_cvt_pk_bf16_f32 v52, v52, v53
	v_mul_f32_e32 v53, v54, v54
	v_fmamk_f32 v53, v53, 0xbdd2d3e7, v228
	v_mul_f32_e32 v53, v54, v53
	v_exp_f32_e32 v53, v53
	s_nop 0
	v_add_f32_e32 v53, 1.0, v53
	v_rcp_f32_e32 v56, v53
	v_mul_f32_e32 v53, v55, v55
	v_fmamk_f32 v53, v53, 0xbdd2d3e7, v228
	v_mul_f32_e32 v53, v55, v53
	v_exp_f32_e32 v53, v53
	s_nop 0
	v_add_f32_e32 v53, 1.0, v53
	v_rcp_f32_e32 v57, v53
	s_nop 0
	v_pk_mul_f32 v[54:55], v[54:55], v[56:57]
	s_nop 0
	v_cvt_pk_bf16_f32 v53, v54, v55
	v_mul_f32_e32 v54, v48, v48
	v_mul_f32_e32 v55, v49, v49
	v_fmamk_f32 v54, v54, 0xbdd2d3e7, v228
	v_fmamk_f32 v55, v55, 0xbdd2d3e7, v228
	v_mul_f32_e32 v54, v48, v54
	v_mul_f32_e32 v55, v49, v55
	v_exp_f32_e32 v54, v54
	v_exp_f32_e32 v55, v55
	v_add_f32_e32 v54, 1.0, v54
	v_add_f32_e32 v55, 1.0, v55
	v_rcp_f32_e32 v54, v54
	v_rcp_f32_e32 v55, v55
	s_nop 0
	v_pk_mul_f32 v[48:49], v[48:49], v[54:55]
	s_nop 0
	v_cvt_pk_bf16_f32 v54, v48, v49
	v_mul_f32_e32 v48, v50, v50
	v_mul_f32_e32 v49, v51, v51
	v_fmamk_f32 v48, v48, 0xbdd2d3e7, v228
	v_fmamk_f32 v49, v49, 0xbdd2d3e7, v228
	v_mul_f32_e32 v48, v50, v48
	v_mul_f32_e32 v49, v51, v49
	v_exp_f32_e32 v48, v48
	v_exp_f32_e32 v49, v49
	v_add_f32_e32 v48, 1.0, v48
	v_add_f32_e32 v49, 1.0, v49
	v_rcp_f32_e32 v48, v48
	v_rcp_f32_e32 v49, v49
	s_nop 0
	v_pk_mul_f32 v[48:49], v[50:51], v[48:49]
	s_nop 0
	v_cvt_pk_bf16_f32 v55, v48, v49
	v_add_u32_e32 v48, v120, v66
	v_ashrrev_i32_e32 v49, 31, v48
	v_lshlrev_b64 v[48:49], 10, v[48:49]
	v_lshl_add_u64 v[48:49], s[46:47], 0, v[48:49]
	v_lshl_add_u64 v[48:49], v[48:49], 0, s[4:5]
	v_lshl_add_u64 v[48:49], v[48:49], 0, v[192:193]
	global_store_dwordx4 v[48:49], v[52:55], off
	v_mul_f32_e32 v48, v44, v44
	v_mul_f32_e32 v49, v45, v45
	v_fmamk_f32 v48, v48, 0xbdd2d3e7, v228
	v_fmamk_f32 v49, v49, 0xbdd2d3e7, v228
	v_mul_f32_e32 v48, v44, v48
	v_mul_f32_e32 v49, v45, v49
	v_exp_f32_e32 v48, v48
	v_exp_f32_e32 v49, v49
	v_add_u32_e32 v50, 0x1200, v145
	v_add_f32_e32 v48, 1.0, v48
	v_add_f32_e32 v49, 1.0, v49
	v_rcp_f32_e32 v48, v48
	v_rcp_f32_e32 v49, v49
	s_nop 0
; __device__ __forceinline__ unsigned cvt_pk_bf16(float lo, float hi) { const cvt_f32x2_t v = {lo, hi}; const cvt_bf16x2_t b = __builtin_convertvector(v, cvt_bf16x2_t); return __builtin_bit_cast(unsigned, b); }
; __device__ __forceinline__ float gelu_tanh(float y) {
;     const float t = 1.5957691216057308f * (y + 0.044715f * y * y * y);
;     return y * __builtin_amdgcn_rcpf(1.0f + __builtin_amdgcn_exp2f(-LOG2E * t));
;     __device__ __forceinline__ void operator()(const f32x4 (&acc)[2][2][4][2], const Unit& u, int wr, int wc, int fr, int fq) const {
;     ...
;                 const int bc = (u.pm & 7) * 256 + ai * 128 + wr * 64 + m * 16 + fr, b = bc >> 6, ch = bc & 63;
; #pragma unroll
;                 for (int bj = 0; bj < 2; ++bj) {
;                     const int nl = (u.pn & 1) * 256 + bj * 128 + wc * 32 + 8 * fq, tau = nl >> 4, c8 = nl & 15;
;                     const f32x4 a = acc[ai][bj][m][0], c = acc[ai][bj][m][1];
;                     u32x4 w; w.x = cvt_pk_bf16(gelu_tanh(a[0]), gelu_tanh(a[1])); w.y = cvt_pk_bf16(gelu_tanh(a[2]), gelu_tanh(a[3]));
;                     w.z = cvt_pk_bf16(gelu_tanh(c[0]), gelu_tanh(c[1])); w.w = cvt_pk_bf16(gelu_tanh(c[2]), gelu_tanh(c[3]));
;                     *(u32x4*)(Z + (size_t)(b * SEQ + ch * CT + tau) * SW + gidx * 16 + c8) = w;
	v_pk_mul_f32 v[44:45], v[44:45], v[48:49]
	s_nop 0
	v_cvt_pk_bf16_f32 v44, v44, v45
	v_mul_f32_e32 v45, v46, v46
	v_fmamk_f32 v45, v45, 0xbdd2d3e7, v228
	v_mul_f32_e32 v45, v46, v45
	v_exp_f32_e32 v45, v45
	s_nop 0
	v_add_f32_e32 v45, 1.0, v45
	v_rcp_f32_e32 v48, v45
	v_mul_f32_e32 v45, v47, v47
	v_fmamk_f32 v45, v45, 0xbdd2d3e7, v228
	v_mul_f32_e32 v45, v47, v45
	v_exp_f32_e32 v45, v45
	s_nop 0
	v_add_f32_e32 v45, 1.0, v45
	v_rcp_f32_e32 v49, v45
	s_nop 0
	v_pk_mul_f32 v[46:47], v[46:47], v[48:49]
	s_nop 0
	v_cvt_pk_bf16_f32 v45, v46, v47
	v_mul_f32_e32 v46, v40, v40
	v_mul_f32_e32 v47, v41, v41
	v_fmamk_f32 v46, v46, 0xbdd2d3e7, v228
	v_fmamk_f32 v47, v47, 0xbdd2d3e7, v228
	v_mul_f32_e32 v46, v40, v46
	v_mul_f32_e32 v47, v41, v47
	v_exp_f32_e32 v46, v46
	v_exp_f32_e32 v47, v47
	v_add_f32_e32 v46, 1.0, v46
	v_add_f32_e32 v47, 1.0, v47
	v_rcp_f32_e32 v46, v46
	v_rcp_f32_e32 v47, v47
	s_nop 0
	v_pk_mul_f32 v[40:41], v[40:41], v[46:47]
	s_nop 0
	v_cvt_pk_bf16_f32 v46, v40, v41
	v_mul_f32_e32 v40, v42, v42
	v_mul_f32_e32 v41, v43, v43
	v_fmamk_f32 v40, v40, 0xbdd2d3e7, v228
	v_fmamk_f32 v41, v41, 0xbdd2d3e7, v228
	v_mul_f32_e32 v40, v42, v40
	v_mul_f32_e32 v41, v43, v41
	v_exp_f32_e32 v40, v40
	v_exp_f32_e32 v41, v41
	v_add_f32_e32 v40, 1.0, v40
	v_add_f32_e32 v41, 1.0, v41
	v_rcp_f32_e32 v40, v40
	v_rcp_f32_e32 v41, v41
	s_nop 0
	v_pk_mul_f32 v[40:41], v[42:43], v[40:41]
	s_nop 0
	v_cvt_pk_bf16_f32 v47, v40, v41
	v_add_u32_e32 v40, v144, v50
	v_ashrrev_i32_e32 v41, 31, v40
	v_lshlrev_b64 v[40:41], 10, v[40:41]
	v_lshl_add_u64 v[40:41], s[46:47], 0, v[40:41]
	v_lshl_add_u64 v[40:41], v[40:41], 0, s[4:5]
	v_lshl_add_u64 v[40:41], v[40:41], 0, v[192:193]
	global_store_dwordx4 v[40:41], v[44:47], off
	v_mul_f32_e32 v40, v36, v36
	v_mul_f32_e32 v41, v37, v37
	v_fmamk_f32 v40, v40, 0xbdd2d3e7, v228
	v_fmamk_f32 v41, v41, 0xbdd2d3e7, v228
	v_mul_f32_e32 v40, v36, v40
	v_mul_f32_e32 v41, v37, v41
	v_exp_f32_e32 v40, v40
	v_exp_f32_e32 v41, v41
	v_add_f32_e32 v40, 1.0, v40
	v_add_f32_e32 v41, 1.0, v41
	v_rcp_f32_e32 v40, v40
	v_rcp_f32_e32 v41, v41
	s_nop 0
	v_pk_mul_f32 v[36:37], v[36:37], v[40:41]
	s_nop 0
	v_cvt_pk_bf16_f32 v36, v36, v37
	v_mul_f32_e32 v37, v38, v38
	v_fmamk_f32 v37, v37, 0xbdd2d3e7, v228
	v_mul_f32_e32 v37, v38, v37
	v_exp_f32_e32 v37, v37
	s_nop 0
	v_add_f32_e32 v37, 1.0, v37
	v_rcp_f32_e32 v40, v37
	v_mul_f32_e32 v37, v39, v39
	v_fmamk_f32 v37, v37, 0xbdd2d3e7, v228
	v_mul_f32_e32 v37, v39, v37
	v_exp_f32_e32 v37, v37
	s_nop 0
	v_add_f32_e32 v37, 1.0, v37
	v_rcp_f32_e32 v41, v37
	s_nop 0
	v_pk_mul_f32 v[38:39], v[38:39], v[40:41]
	s_nop 0
	v_cvt_pk_bf16_f32 v37, v38, v39
	v_mul_f32_e32 v38, v32, v32
	v_mul_f32_e32 v39, v33, v33
	v_fmamk_f32 v38, v38, 0xbdd2d3e7, v228
	v_fmamk_f32 v39, v39, 0xbdd2d3e7, v228
	v_mul_f32_e32 v38, v32, v38
	v_mul_f32_e32 v39, v33, v39
	v_exp_f32_e32 v38, v38
	v_exp_f32_e32 v39, v39
	v_add_f32_e32 v38, 1.0, v38
	v_add_f32_e32 v39, 1.0, v39
	v_rcp_f32_e32 v38, v38
	v_rcp_f32_e32 v39, v39
	s_nop 0
	v_pk_mul_f32 v[32:33], v[32:33], v[38:39]
	s_nop 0
	v_cvt_pk_bf16_f32 v38, v32, v33
	v_mul_f32_e32 v32, v34, v34
	v_mul_f32_e32 v33, v35, v35
	v_fmamk_f32 v32, v32, 0xbdd2d3e7, v228
	v_fmamk_f32 v33, v33, 0xbdd2d3e7, v228
	v_mul_f32_e32 v32, v34, v32
	v_mul_f32_e32 v33, v35, v33
	v_exp_f32_e32 v32, v32
	v_exp_f32_e32 v33, v33
	v_add_f32_e32 v32, 1.0, v32
	v_add_f32_e32 v33, 1.0, v33
	v_rcp_f32_e32 v32, v32
	v_rcp_f32_e32 v33, v33
	s_nop 0
	v_pk_mul_f32 v[32:33], v[34:35], v[32:33]
	s_nop 0
	v_cvt_pk_bf16_f32 v39, v32, v33
	v_add_u32_e32 v32, v120, v50
	v_ashrrev_i32_e32 v33, 31, v32
	v_lshlrev_b64 v[32:33], 10, v[32:33]
	v_lshl_add_u64 v[32:33], s[46:47], 0, v[32:33]
	v_lshl_add_u64 v[32:33], v[32:33], 0, s[4:5]
	v_lshl_add_u64 v[32:33], v[32:33], 0, v[192:193]
	global_store_dwordx4 v[32:33], v[36:39], off
	v_mul_f32_e32 v32, v28, v28
	v_mul_f32_e32 v33, v29, v29
	v_fmamk_f32 v32, v32, 0xbdd2d3e7, v228
	v_fmamk_f32 v33, v33, 0xbdd2d3e7, v228
	v_mul_f32_e32 v32, v28, v32
	v_mul_f32_e32 v33, v29, v33
	v_exp_f32_e32 v32, v32
	v_exp_f32_e32 v33, v33
	v_add_u32_e32 v34, 0x1400, v145
	v_add_f32_e32 v32, 1.0, v32
	v_add_f32_e32 v33, 1.0, v33
	v_rcp_f32_e32 v32, v32
	v_rcp_f32_e32 v33, v33
	s_nop 0
	v_pk_mul_f32 v[28:29], v[28:29], v[32:33]
	s_nop 0
	v_cvt_pk_bf16_f32 v28, v28, v29
	v_mul_f32_e32 v29, v30, v30
	v_fmamk_f32 v29, v29, 0xbdd2d3e7, v228
	v_mul_f32_e32 v29, v30, v29
	v_exp_f32_e32 v29, v29
	s_nop 0
	v_add_f32_e32 v29, 1.0, v29
	v_rcp_f32_e32 v32, v29
	v_mul_f32_e32 v29, v31, v31
	v_fmamk_f32 v29, v29, 0xbdd2d3e7, v228
	v_mul_f32_e32 v29, v31, v29
	v_exp_f32_e32 v29, v29
	s_nop 0
	v_add_f32_e32 v29, 1.0, v29
	v_rcp_f32_e32 v33, v29
	s_nop 0
	v_pk_mul_f32 v[30:31], v[30:31], v[32:33]
	s_nop 0
	v_cvt_pk_bf16_f32 v29, v30, v31
	v_mul_f32_e32 v30, v24, v24
	v_mul_f32_e32 v31, v25, v25
	v_fmamk_f32 v30, v30, 0xbdd2d3e7, v228
	v_fmamk_f32 v31, v31, 0xbdd2d3e7, v228
	v_mul_f32_e32 v30, v24, v30
	v_mul_f32_e32 v31, v25, v31
	v_exp_f32_e32 v30, v30
	v_exp_f32_e32 v31, v31
	v_add_f32_e32 v30, 1.0, v30
	v_add_f32_e32 v31, 1.0, v31
	v_rcp_f32_e32 v30, v30
	v_rcp_f32_e32 v31, v31
	s_nop 0
	v_pk_mul_f32 v[24:25], v[24:25], v[30:31]
	s_nop 0
	v_cvt_pk_bf16_f32 v30, v24, v25
	v_mul_f32_e32 v24, v26, v26
	v_mul_f32_e32 v25, v27, v27
	v_fmamk_f32 v24, v24, 0xbdd2d3e7, v228
	v_fmamk_f32 v25, v25, 0xbdd2d3e7, v228
	v_mul_f32_e32 v24, v26, v24
	v_mul_f32_e32 v25, v27, v25
	v_exp_f32_e32 v24, v24
	v_exp_f32_e32 v25, v25
	v_add_f32_e32 v24, 1.0, v24
	v_add_f32_e32 v25, 1.0, v25
	v_rcp_f32_e32 v24, v24
	v_rcp_f32_e32 v25, v25
	s_nop 0
	v_pk_mul_f32 v[24:25], v[26:27], v[24:25]
	s_nop 0
	v_cvt_pk_bf16_f32 v31, v24, v25
; __device__ __forceinline__ unsigned cvt_pk_bf16(float lo, float hi) { const cvt_f32x2_t v = {lo, hi}; const cvt_bf16x2_t b = __builtin_convertvector(v, cvt_bf16x2_t); return __builtin_bit_cast(unsigned, b); }
; #define PG8_BAR __builtin_amdgcn_s_barrier()
; template <class Epi, class Sched, bool ALIGN_EPI>
; __device__ __forceinline__ void gemm_phase(LAS unsigned char* lds, const Gemm g, const Sched& S, const Epi& E) {
;     ...
;         if (!has_next) break;
; #pragma unroll
;         for (int a = 0; a < 2; ++a)
; #pragma unroll
;             for (int b = 0; b < 2; ++b)
; #pragma unroll
;                 for (int m = 0; m < 4; ++m)
; #pragma unroll
;                     for (int n = 0; n < 2; ++n) acc[a][b][m][n] = (f32x4){0.f, 0.f, 0.f, 0.f};
;         cur = nxt; cA = nA; cB = nB; ++ui;
;         if constexpr (ALIGN_EPI) { if (wr == 1) PG8_BAR; }
;     __device__ __forceinline__ void operator()(const f32x4 (&acc)[2][2][4][2], const Unit& u, int wr, int wc, int fr, int fq) const {
;     ...
;                 const int bc = (u.pm & 7) * 256 + ai * 128 + wr * 64 + m * 16 + fr, b = bc >> 6, ch = bc & 63;
; #pragma unroll
;                 for (int bj = 0; bj < 2; ++bj) {
;                     const int nl = (u.pn & 1) * 256 + bj * 128 + wc * 32 + 8 * fq, tau = nl >> 4, c8 = nl & 15;
;                     const f32x4 a = acc[ai][bj][m][0], c = acc[ai][bj][m][1];
;                     u32x4 w; w.x = cvt_pk_bf16(gelu_tanh(a[0]), gelu_tanh(a[1])); w.y = cvt_pk_bf16(gelu_tanh(a[2]), gelu_tanh(a[3]));
;                     w.z = cvt_pk_bf16(gelu_tanh(c[0]), gelu_tanh(c[1])); w.w = cvt_pk_bf16(gelu_tanh(c[2]), gelu_tanh(c[3]));
;                     *(u32x4*)(Z + (size_t)(b * SEQ + ch * CT + tau) * SW + gidx * 16 + c8) = w;
	v_add_u32_e32 v24, v144, v34
	v_ashrrev_i32_e32 v25, 31, v24
	v_lshlrev_b64 v[24:25], 10, v[24:25]
	v_lshl_add_u64 v[24:25], s[46:47], 0, v[24:25]
	v_lshl_add_u64 v[24:25], v[24:25], 0, s[4:5]
	v_lshl_add_u64 v[24:25], v[24:25], 0, v[192:193]
	global_store_dwordx4 v[24:25], v[28:31], off
	v_mul_f32_e32 v24, v20, v20
	v_mul_f32_e32 v25, v21, v21
	v_fmamk_f32 v24, v24, 0xbdd2d3e7, v228
	v_fmamk_f32 v25, v25, 0xbdd2d3e7, v228
	v_mul_f32_e32 v24, v20, v24
	v_mul_f32_e32 v25, v21, v25
	v_exp_f32_e32 v24, v24
	v_exp_f32_e32 v25, v25
	v_add_f32_e32 v24, 1.0, v24
	v_add_f32_e32 v25, 1.0, v25
	v_rcp_f32_e32 v24, v24
	v_rcp_f32_e32 v25, v25
	s_nop 0
	v_pk_mul_f32 v[20:21], v[20:21], v[24:25]
	s_nop 0
	v_cvt_pk_bf16_f32 v20, v20, v21
	v_mul_f32_e32 v21, v22, v22
	v_fmamk_f32 v21, v21, 0xbdd2d3e7, v228
	v_mul_f32_e32 v21, v22, v21
	v_exp_f32_e32 v21, v21
	s_nop 0
	v_add_f32_e32 v21, 1.0, v21
	v_rcp_f32_e32 v24, v21
	v_mul_f32_e32 v21, v23, v23
	v_fmamk_f32 v21, v21, 0xbdd2d3e7, v228
	v_mul_f32_e32 v21, v23, v21
	v_exp_f32_e32 v21, v21
	s_nop 0
	v_add_f32_e32 v21, 1.0, v21
	v_rcp_f32_e32 v25, v21
	s_nop 0
	v_pk_mul_f32 v[22:23], v[22:23], v[24:25]
	s_nop 0
	v_cvt_pk_bf16_f32 v21, v22, v23
	v_mul_f32_e32 v22, v16, v16
	v_mul_f32_e32 v23, v17, v17
	v_fmamk_f32 v22, v22, 0xbdd2d3e7, v228
	v_fmamk_f32 v23, v23, 0xbdd2d3e7, v228
	v_mul_f32_e32 v22, v16, v22
	v_mul_f32_e32 v23, v17, v23
	v_exp_f32_e32 v22, v22
	v_exp_f32_e32 v23, v23
	v_add_f32_e32 v22, 1.0, v22
	v_add_f32_e32 v23, 1.0, v23
	v_rcp_f32_e32 v22, v22
	v_rcp_f32_e32 v23, v23
	s_nop 0
	v_pk_mul_f32 v[16:17], v[16:17], v[22:23]
	s_nop 0
	v_cvt_pk_bf16_f32 v22, v16, v17
	v_mul_f32_e32 v16, v18, v18
	v_mul_f32_e32 v17, v19, v19
	v_fmamk_f32 v16, v16, 0xbdd2d3e7, v228
	v_fmamk_f32 v17, v17, 0xbdd2d3e7, v228
	v_mul_f32_e32 v16, v18, v16
	v_mul_f32_e32 v17, v19, v17
	v_exp_f32_e32 v16, v16
	v_exp_f32_e32 v17, v17
	v_add_f32_e32 v16, 1.0, v16
	v_add_f32_e32 v17, 1.0, v17
	v_rcp_f32_e32 v16, v16
	v_rcp_f32_e32 v17, v17
	s_nop 0
	v_pk_mul_f32 v[16:17], v[18:19], v[16:17]
	s_nop 0
	v_cvt_pk_bf16_f32 v23, v16, v17
	v_add_u32_e32 v16, v120, v34
	v_ashrrev_i32_e32 v17, 31, v16
	v_lshlrev_b64 v[16:17], 10, v[16:17]
	v_lshl_add_u64 v[16:17], s[46:47], 0, v[16:17]
	v_lshl_add_u64 v[16:17], v[16:17], 0, s[4:5]
	v_lshl_add_u64 v[16:17], v[16:17], 0, v[192:193]
	global_store_dwordx4 v[16:17], v[20:23], off
	v_mul_f32_e32 v16, v12, v12
	v_mul_f32_e32 v17, v13, v13
	v_fmamk_f32 v16, v16, 0xbdd2d3e7, v228
	v_fmamk_f32 v17, v17, 0xbdd2d3e7, v228
	v_mul_f32_e32 v16, v12, v16
	v_mul_f32_e32 v17, v13, v17
	v_exp_f32_e32 v16, v16
	v_exp_f32_e32 v17, v17
	v_add_u32_e32 v18, 0x1600, v145
	v_add_f32_e32 v16, 1.0, v16
	v_add_f32_e32 v17, 1.0, v17
	v_rcp_f32_e32 v16, v16
	v_rcp_f32_e32 v17, v17
	s_nop 0
	v_pk_mul_f32 v[12:13], v[12:13], v[16:17]
	s_nop 0
	v_cvt_pk_bf16_f32 v12, v12, v13
	v_mul_f32_e32 v13, v14, v14
	v_fmamk_f32 v13, v13, 0xbdd2d3e7, v228
	v_mul_f32_e32 v13, v14, v13
	v_exp_f32_e32 v13, v13
	s_nop 0
	v_add_f32_e32 v13, 1.0, v13
	v_rcp_f32_e32 v16, v13
	v_mul_f32_e32 v13, v15, v15
	v_fmamk_f32 v13, v13, 0xbdd2d3e7, v228
	v_mul_f32_e32 v13, v15, v13
	v_exp_f32_e32 v13, v13
	s_nop 0
	v_add_f32_e32 v13, 1.0, v13
	v_rcp_f32_e32 v17, v13
	s_nop 0
	v_pk_mul_f32 v[14:15], v[14:15], v[16:17]
	s_nop 0
	v_cvt_pk_bf16_f32 v13, v14, v15
	v_mul_f32_e32 v14, v8, v8
	v_mul_f32_e32 v15, v9, v9
	v_fmamk_f32 v14, v14, 0xbdd2d3e7, v228
	v_fmamk_f32 v15, v15, 0xbdd2d3e7, v228
	v_mul_f32_e32 v14, v8, v14
	v_mul_f32_e32 v15, v9, v15
	v_exp_f32_e32 v14, v14
	v_exp_f32_e32 v15, v15
	v_add_f32_e32 v14, 1.0, v14
	v_add_f32_e32 v15, 1.0, v15
	v_rcp_f32_e32 v14, v14
	v_rcp_f32_e32 v15, v15
	s_nop 0
	v_pk_mul_f32 v[8:9], v[8:9], v[14:15]
	s_nop 0
	v_cvt_pk_bf16_f32 v14, v8, v9
	v_mul_f32_e32 v8, v10, v10
	v_mul_f32_e32 v9, v11, v11
	v_fmamk_f32 v8, v8, 0xbdd2d3e7, v228
	v_fmamk_f32 v9, v9, 0xbdd2d3e7, v228
	v_mul_f32_e32 v8, v10, v8
	v_mul_f32_e32 v9, v11, v9
	v_exp_f32_e32 v8, v8
	v_exp_f32_e32 v9, v9
	v_add_f32_e32 v8, 1.0, v8
	v_add_f32_e32 v9, 1.0, v9
	v_rcp_f32_e32 v8, v8
	v_rcp_f32_e32 v9, v9
	s_nop 0
	v_pk_mul_f32 v[8:9], v[10:11], v[8:9]
	s_nop 0
	v_cvt_pk_bf16_f32 v15, v8, v9
	v_add_u32_e32 v8, v144, v18
	v_ashrrev_i32_e32 v9, 31, v8
	v_lshlrev_b64 v[8:9], 10, v[8:9]
	v_lshl_add_u64 v[8:9], s[46:47], 0, v[8:9]
	v_lshl_add_u64 v[8:9], v[8:9], 0, s[4:5]
	v_lshl_add_u64 v[8:9], v[8:9], 0, v[192:193]
	global_store_dwordx4 v[8:9], v[12:15], off
	v_mul_f32_e32 v8, v4, v4
	v_mul_f32_e32 v9, v5, v5
	v_fmamk_f32 v8, v8, 0xbdd2d3e7, v228
	v_fmamk_f32 v9, v9, 0xbdd2d3e7, v228
	v_mul_f32_e32 v8, v4, v8
	v_mul_f32_e32 v9, v5, v9
	v_exp_f32_e32 v8, v8
	v_exp_f32_e32 v9, v9
	v_add_f32_e32 v8, 1.0, v8
	v_add_f32_e32 v9, 1.0, v9
	v_rcp_f32_e32 v8, v8
	v_rcp_f32_e32 v9, v9
	s_nop 0
	v_pk_mul_f32 v[4:5], v[4:5], v[8:9]
	s_nop 0
	v_cvt_pk_bf16_f32 v4, v4, v5
	v_mul_f32_e32 v5, v6, v6
	v_fmamk_f32 v5, v5, 0xbdd2d3e7, v228
	v_mul_f32_e32 v5, v6, v5
	v_exp_f32_e32 v5, v5
	s_nop 0
	v_add_f32_e32 v5, 1.0, v5
	v_rcp_f32_e32 v8, v5
	v_mul_f32_e32 v5, v7, v7
	v_fmamk_f32 v5, v5, 0xbdd2d3e7, v228
	v_mul_f32_e32 v5, v7, v5
	v_exp_f32_e32 v5, v5
	s_nop 0
	v_add_f32_e32 v5, 1.0, v5
	v_rcp_f32_e32 v9, v5
	s_nop 0
	v_pk_mul_f32 v[6:7], v[6:7], v[8:9]
	s_nop 0
	v_cvt_pk_bf16_f32 v5, v6, v7
	v_mul_f32_e32 v6, v0, v0
	v_mul_f32_e32 v7, v1, v1
	v_fmamk_f32 v6, v6, 0xbdd2d3e7, v228
	v_fmamk_f32 v7, v7, 0xbdd2d3e7, v228
	v_mul_f32_e32 v6, v0, v6
	v_mul_f32_e32 v7, v1, v7
	v_exp_f32_e32 v6, v6
	v_exp_f32_e32 v7, v7
	v_add_f32_e32 v6, 1.0, v6
	v_add_f32_e32 v7, 1.0, v7
	v_rcp_f32_e32 v6, v6
	v_rcp_f32_e32 v7, v7
	s_nop 0
	v_pk_mul_f32 v[0:1], v[0:1], v[6:7]
	s_nop 0
	v_cvt_pk_bf16_f32 v6, v0, v1
	v_mul_f32_e32 v0, v2, v2
	v_mul_f32_e32 v1, v3, v3
	v_fmamk_f32 v0, v0, 0xbdd2d3e7, v228
	v_fmamk_f32 v1, v1, 0xbdd2d3e7, v228
	v_mul_f32_e32 v0, v2, v0
	v_mul_f32_e32 v1, v3, v1
	v_exp_f32_e32 v0, v0
	v_exp_f32_e32 v1, v1
	v_add_f32_e32 v0, 1.0, v0
	v_add_f32_e32 v1, 1.0, v1
	v_rcp_f32_e32 v0, v0
	v_rcp_f32_e32 v1, v1
	s_nop 0
	v_pk_mul_f32 v[0:1], v[2:3], v[0:1]
	s_nop 0
	v_cvt_pk_bf16_f32 v7, v0, v1
	v_add_u32_e32 v0, v120, v18
	v_ashrrev_i32_e32 v1, 31, v0
	v_lshlrev_b64 v[0:1], 10, v[0:1]
	v_lshl_add_u64 v[0:1], s[46:47], 0, v[0:1]
	v_lshl_add_u64 v[0:1], v[0:1], 0, s[4:5]
	v_lshl_add_u64 v[0:1], v[0:1], 0, v[192:193]
	s_mov_b64 s[4:5], -1
	global_store_dwordx4 v[0:1], v[4:7], off
	s_cbranch_vccnz .LBB0_426
	s_andn2_b64 vcc, exec, s[22:23]
	s_cbranch_vccnz .LBB0_425
	s_barrier
	s_branch .LBB0_425
